# barriers behind G2/G4 keep the cross-XCD rendezvous but skip the L2 write-back (their products are only read on the same XCC before the next flushing barrier)
# speedup vs baseline: 1.0186x; 1.0082x over previous
.LBB0_860:
	v_readlane_b32 s28, v254, 56
	s_nop 0
	s_and_b32 s29, s28, 4
	s_cbranch_scc1 .Lgb_cand
	s_mov_b32 s28, 0
	s_branch .Lgb_decided
.Lgb_cand:
	s_and_b32 s28, s28, 1
	s_add_u32 s28, s28, 1
	v_readlane_b32 s29, v255, 20
	s_nop 0
	s_cmp_lg_u32 s29, 0
	s_cbranch_scc1 .Lgb_known
	s_mov_b64 s[26:27], 0x5000
	v_lshl_add_u64 v[12:13], v[2:3], 0, s[26:27]
	flat_load_dword v12, v[12:13] sc1
	s_waitcnt vmcnt(0) lgkmcnt(0)
	v_readfirstlane_b32 s29, v12
	s_nop 0
	s_cmp_eq_u32 s29, 0
	s_cselect_b32 s29, 1, 2
	s_nop 0
	v_writelane_b32 v255, s29, 20
.Lgb_known:
	s_cmp_eq_u32 s29, 1
	s_cselect_b32 s28, s28, 0

.Lgb_full:
	v_cmp_ne_u32_e32 vcc, v7, v8
	s_cbranch_vccnz .Lgb_arrived
	s_cmp_eq_u32 s28, 2
	s_cbranch_scc1 .Lgb_noflush
	buffer_wbl2 sc1
	s_waitcnt vmcnt(0)
.Lgb_noflush:
	flat_atomic_add v[10:11], v223 offset:1024
	buffer_inv sc1
	s_branch .Lgb_poll
